# write-through (sc1) on all residual-stream (x f32 and xb bf16) stores of the Resid epilogue to shrink the L2 writeback at the 12 FFN-out / mix-out seams (on v52)
# speedup vs baseline: 1.0148x; 1.0148x over previous
.LBB0_381:
	v_lshl_add_u32 v184, s25, 8, v167
	v_lshl_or_b32 v180, s24, 8, v202
	v_ashrrev_i32_e32 v181, 31, v180
	v_ashrrev_i32_e32 v185, 31, v184
	v_or_b32_e32 v194, 16, v184
	v_lshl_add_u64 v[182:183], v[180:181], 1, s[0:1]
	v_lshlrev_b64 v[198:199], 11, v[184:185]
	v_ashrrev_i32_e32 v195, 31, v194
	v_or_b32_e32 v190, 32, v184
	v_lshl_add_u64 v[128:129], v[182:183], 0, v[198:199]
	v_lshlrev_b64 v[196:197], 11, v[194:195]
	v_ashrrev_i32_e32 v191, 31, v190
	v_or_b32_e32 v186, 48, v184
	global_load_dwordx4 v[206:209], v[128:129], off
	global_load_dwordx4 v[152:155], v[128:129], off offset:256
	v_lshl_add_u64 v[128:129], v[182:183], 0, v[196:197]
	v_lshlrev_b64 v[192:193], 11, v[190:191]
	v_ashrrev_i32_e32 v187, 31, v186
	global_load_dwordx4 v[148:151], v[128:129], off
	global_load_dwordx4 v[144:147], v[128:129], off offset:256
	v_lshl_add_u64 v[128:129], v[182:183], 0, v[192:193]
	v_lshlrev_b64 v[188:189], 11, v[186:187]
	global_load_dwordx4 v[140:143], v[128:129], off
	global_load_dwordx4 v[136:139], v[128:129], off offset:256
	v_lshl_add_u64 v[128:129], v[182:183], 0, v[188:189]
	global_load_dwordx4 v[132:135], v[128:129], off
	s_nop 0
	global_load_dwordx4 v[128:131], v[128:129], off offset:256
	v_lshl_add_u64 v[250:251], v[182:183], 0, v[198:199]
	v_add_co_u32_e32 v250, vcc, 0x40000, v250
	s_nop 1
	v_addc_co_u32_e32 v251, vcc, 0, v251, vcc
	global_load_dwordx4 v[210:213], v[250:251], off
	global_load_dwordx4 v[222:225], v[250:251], off offset:256
	v_add_co_u32_e32 v250, vcc, 0x8000, v250
	s_nop 1
	v_addc_co_u32_e32 v251, vcc, 0, v251, vcc
	global_load_dwordx4 v[234:237], v[250:251], off
	global_load_dwordx4 v[230:233], v[250:251], off offset:256
	v_add_co_u32_e32 v250, vcc, 0x8000, v250
	s_nop 1
	v_addc_co_u32_e32 v251, vcc, 0, v251, vcc
	global_load_dwordx4 v[242:245], v[250:251], off
	global_load_dwordx4 v[246:249], v[250:251], off offset:256
	v_cndmask_b32_e64 v162, 0, 1, s[16:17]
	v_cmp_ne_u32_e64 s[40:41], 1, v162
	v_lshlrev_b64 v[162:163], 12, v[184:185]
	v_mov_b32_e32 v173, v172
	v_lshl_add_u64 v[162:163], s[12:13], 0, v[162:163]
	s_andn2_b64 vcc, exec, s[16:17]
	s_waitcnt vmcnt(0)
	v_lshlrev_b32_e32 v164, 16, v206
	v_and_b32_e32 v165, 0xffff0000, v206
	v_lshlrev_b32_e32 v200, 16, v207
	v_and_b32_e32 v201, 0xffff0000, v207
	v_lshlrev_b32_e32 v206, 16, v208
	v_and_b32_e32 v207, 0xffff0000, v208
	v_lshlrev_b32_e32 v208, 16, v209
	v_and_b32_e32 v209, 0xffff0000, v209
	v_pk_fma_f32 v[126:127], v[172:173], v[126:127], v[200:201]
	v_pk_fma_f32 v[124:125], v[174:175], v[124:125], v[164:165]
	v_pk_fma_f32 v[122:123], v[172:173], v[122:123], v[208:209]
	v_pk_fma_f32 v[120:121], v[174:175], v[120:121], v[206:207]
	v_lshl_add_u64 v[200:201], v[180:181], 2, v[162:163]
	s_cbranch_vccnz .LBB0_383
	s_mov_b64 s[82:83], 0
	global_store_dwordx4 v[200:201], v[124:127], off sc1
	global_store_dwordx4 v[200:201], v[120:123], off offset:16 sc1
	s_branch .LBB0_384

.LBB0_415:
	s_or_b64 exec, exec, s[82:83]
	v_add_u32_e32 v104, 0x80, v184
	v_ashrrev_i32_e32 v105, 31, v104
	v_add_u32_e32 v100, 0x90, v184
	v_lshlrev_b64 v[106:107], 11, v[104:105]
	v_ashrrev_i32_e32 v101, 31, v100
	v_add_u32_e32 v96, 0xa0, v184
	s_waitcnt lgkmcnt(0)
	v_lshl_add_u64 v[64:65], v[182:183], 0, v[106:107]
	v_lshlrev_b64 v[102:103], 11, v[100:101]
	v_ashrrev_i32_e32 v97, 31, v96
	v_add_u32_e32 v92, 0xb0, v184
	v_mov_b32_e32 v108, v210
	v_mov_b32_e32 v109, v211
	v_mov_b32_e32 v110, v212
	v_mov_b32_e32 v111, v213
	v_mov_b32_e32 v88, v222
	v_mov_b32_e32 v89, v223
	v_mov_b32_e32 v90, v224
	v_mov_b32_e32 v91, v225
	v_lshl_add_u64 v[64:65], v[182:183], 0, v[102:103]
	v_lshlrev_b64 v[98:99], 11, v[96:97]
	v_ashrrev_i32_e32 v93, 31, v92
	v_mov_b32_e32 v84, v234
	v_mov_b32_e32 v85, v235
	v_mov_b32_e32 v86, v236
	v_mov_b32_e32 v87, v237
	v_mov_b32_e32 v80, v230
	v_mov_b32_e32 v81, v231
	v_mov_b32_e32 v82, v232
	v_mov_b32_e32 v83, v233
	v_lshl_add_u64 v[64:65], v[182:183], 0, v[98:99]
	v_lshlrev_b64 v[94:95], 11, v[92:93]
	v_mov_b32_e32 v76, v242
	v_mov_b32_e32 v77, v243
	v_mov_b32_e32 v78, v244
	v_mov_b32_e32 v79, v245
	v_mov_b32_e32 v72, v246
	v_mov_b32_e32 v73, v247
	v_mov_b32_e32 v74, v248
	v_mov_b32_e32 v75, v249
	v_lshl_add_u64 v[64:65], v[182:183], 0, v[94:95]
	global_load_dwordx4 v[68:71], v[64:65], off
	s_nop 0
	global_load_dwordx4 v[64:67], v[64:65], off offset:256
	v_lshlrev_b64 v[112:113], 12, v[104:105]
	v_mov_b32_e32 v173, v172
	v_lshl_add_u64 v[112:113], s[12:13], 0, v[112:113]
	s_and_b64 vcc, exec, s[40:41]
	s_waitcnt vmcnt(7)
	v_lshlrev_b32_e32 v114, 16, v108
	v_and_b32_e32 v115, 0xffff0000, v108
	v_lshlrev_b32_e32 v108, 16, v109
	v_and_b32_e32 v109, 0xffff0000, v109
	v_lshlrev_b32_e32 v116, 16, v110
	v_and_b32_e32 v117, 0xffff0000, v110
	v_lshlrev_b32_e32 v110, 16, v111
	v_and_b32_e32 v111, 0xffff0000, v111
	v_pk_fma_f32 v[62:63], v[172:173], v[62:63], v[108:109]
	v_pk_fma_f32 v[60:61], v[174:175], v[60:61], v[114:115]
	v_pk_fma_f32 v[58:59], v[172:173], v[58:59], v[110:111]
	v_pk_fma_f32 v[56:57], v[174:175], v[56:57], v[116:117]
	v_lshl_add_u64 v[108:109], v[180:181], 2, v[112:113]
	s_cbranch_vccnz .LBB0_457
	global_store_dwordx4 v[108:109], v[60:63], off sc1
	global_store_dwordx4 v[108:109], v[56:59], off offset:16 sc1
	v_lshl_add_u64 v[106:107], s[0:1], 0, v[106:107]
	v_lshl_add_u64 v[106:107], v[180:181], 1, v[106:107]
	s_cbranch_execnz .LBB0_418
